# P8 GEMM: first K-loop iteration peeled (SrcC=0, no zeroing moves, first two waits relaxed by the 16 epilogue stores), on the saddr-epilogue version
# speedup vs baseline: 1.0021x; 1.0021x over previous
.LBB0_754:
	v_readlane_b32 s4, v252, 6
	v_readlane_b32 s5, v252, 7
	s_cmp_le_i32 s4, s2
	s_cselect_b64 s[4:5], -1, 0
	s_and_b64 s[10:11], s[4:5], s[0:1]
	v_readlane_b32 s0, v254, 36
	v_readlane_b32 s1, v254, 37
	s_cmp_eq_u32 s0, 3
	s_cselect_b64 s[0:1], -1, 0
	s_andn2_b64 vcc, exec, s[10:11]
	s_cbranch_vccnz .LBB0_877
	s_mov_b32 s98, 0
	v_readlane_b32 s4, v254, 20
	v_readlane_b32 s2, v252, 2
	v_readlane_b32 s38, v252, 15
	v_mov_b32_e32 v0, s4
	s_waitcnt vmcnt(19)
	ds_read_b64 v[2:3], v0
	v_readlane_b32 s4, v254, 30
	s_waitcnt lgkmcnt(0)
	v_readfirstlane_b32 s13, v3
	v_mov_b32_e32 v0, s4
	v_readfirstlane_b32 s12, v2
	s_waitcnt vmcnt(9)
	ds_read2_b64 v[2:5], v0 offset1:1
	v_mov_b32_e32 v0, v1
	v_readlane_b32 s4, v253, 56
	v_mbcnt_lo_u32_b32 v0, -1, v0
	v_readlane_b32 s5, v253, 57
	s_waitcnt lgkmcnt(0)
	v_readfirstlane_b32 s21, v3
	v_readfirstlane_b32 s20, v2
	v_readfirstlane_b32 s23, v5
	v_readfirstlane_b32 s22, v4
	s_waitcnt vmcnt(8)
	v_mbcnt_hi_u32_b32 v20, -1, v0
	s_andn2_b64 vcc, exec, s[4:5]
	s_cbranch_vccnz .LBB0_803
	v_readlane_b32 s4, v254, 36
	v_readlane_b32 s5, v254, 37
	s_mul_hi_u32 s6, s4, 0x2c00000
	s_mul_i32 s7, s4, 0x2c00000
	s_add_u32 s4, s12, 0x28d00000
	s_addc_u32 s5, s13, 0
	s_add_u32 s7, s12, s7
	s_addc_u32 s8, s13, s6
	s_add_u32 s6, s7, 0x18500000
	s_addc_u32 s7, s8, 0
	s_lshl_b32 s8, s38, 10
	v_lshl_add_u32 v0, v20, 4, s8
	v_add_u32_e32 v2, 0x2000, v0
	v_ashrrev_i32_e32 v3, 31, v2
	v_lshrrev_b32_e32 v3, 22, v3
	v_add_u32_e32 v3, v2, v3
	v_ashrrev_i32_e32 v10, 10, v3
	v_mul_i32_i24_e32 v3, 0x400, v10
	v_sub_u32_e32 v2, v2, v3
	v_lshrrev_b32_e32 v3, 4, v2
	v_bitop3_b32 v2, v3, v2, 32 bitop3:0x6c
	v_ashrrev_i32_e32 v3, 31, v2
	v_lshrrev_b32_e32 v3, 26, v3
	v_add_u32_e32 v3, v2, v3
	v_lshlrev_b32_e32 v5, 3, v10
	v_ashrrev_i32_e32 v4, 6, v3
	v_and_b32_e32 v5, -16, v5
	v_and_b32_e32 v3, 0xffc0, v3
	v_add_u32_e32 v5, v4, v5
	v_sub_u32_e32 v2, v2, v3
	v_and_b32_e32 v4, 3, v4
	s_mov_b32 s9, 0xfffe0
	v_lshrrev_b32_e32 v6, 2, v5
	v_lshlrev_b32_e32 v7, 1, v5
	v_lshrrev_b16_e32 v3, 7, v2
	v_and_or_b32 v4, v5, s9, v4
	v_and_b32_e32 v6, 4, v6
	v_and_b32_e32 v7, 24, v7
	v_and_b32_e32 v3, 1, v3
	v_or3_b32 v4, v4, v6, v7
	v_add_u16_e32 v2, v2, v3
	v_mov_b32_e32 v7, 1
	v_lshlrev_b32_e32 v6, 5, v10
	v_ashrrev_i16_sdwa v2, v7, sext(v2) dst_sel:DWORD dst_unused:UNUSED_PAD src0_sel:DWORD src1_sel:BYTE_0
	v_lshlrev_b32_e32 v3, 2, v5
	v_and_b32_e32 v6, 32, v6
	v_bfe_i32 v11, v2, 0, 16
	v_and_b32_e32 v13, 64, v5
	s_waitcnt vmcnt(0)
	v_and_b32_e32 v14, 60, v3
	v_bfe_u32 v15, v5, 4, 2
	v_add_lshl_u32 v2, v6, v11, 1
	v_or3_b32 v3, v13, v14, v15
	v_lshl_add_u32 v174, v4, 12, v2
	v_lshl_add_u32 v176, v3, 12, v2
	v_ashrrev_i32_e32 v2, 31, v0
	v_lshrrev_b32_e32 v2, 22, v2
	v_add_u32_e32 v2, v0, v2
	v_ashrrev_i32_e32 v12, 10, v2
	v_mul_i32_i24_e32 v2, 0x400, v12
	v_sub_u32_e32 v0, v0, v2
	v_lshrrev_b32_e32 v2, 4, v0
	v_bitop3_b32 v0, v2, v0, 32 bitop3:0x6c
	v_ashrrev_i32_e32 v2, 31, v0
	v_lshrrev_b32_e32 v2, 26, v2
	v_add_u32_e32 v2, v0, v2
	v_lshlrev_b32_e32 v4, 3, v12
	v_ashrrev_i32_e32 v3, 6, v2
	v_and_b32_e32 v4, -16, v4
	v_add_u32_e32 v4, v3, v4
	v_and_b32_e32 v3, 3, v3
	v_lshrrev_b32_e32 v5, 2, v4
	v_lshlrev_b32_e32 v6, 1, v4
	v_and_b32_e32 v2, 0xc0, v2
	v_and_or_b32 v3, v4, s9, v3
	v_and_b32_e32 v5, 4, v5
	v_and_b32_e32 v6, 24, v6
	v_sub_u32_e32 v0, v0, v2
	s_ashr_i32 s30, s38, 2
	v_or3_b32 v3, v3, v5, v6
	v_lshlrev_b32_e32 v5, 5, v12
	v_ashrrev_i16_sdwa v0, v7, sext(v0) dst_sel:DWORD dst_unused:UNUSED_PAD src0_sel:DWORD src1_sel:BYTE_0
	v_readlane_b32 s14, v253, 62
	v_and_b32_e32 v5, 32, v5
	v_bfe_i32 v16, v0, 0, 16
	v_readlane_b32 s15, v253, 63
	s_add_u32 s64, s6, s14
	v_add_lshl_u32 v2, v5, v16, 1
	s_addc_u32 s65, s7, s15
	s_add_i32 s9, s8, 0
	v_lshl_add_u32 v0, v3, 12, v2
	s_add_i32 m0, s9, 0x10000
	v_lshlrev_b32_e32 v3, 2, v4
	global_load_lds_dwordx4 v0, s[64:65]
	s_add_i32 m0, s9, 0x12000
	s_add_u32 s14, s64, 0x80000
	global_load_lds_dwordx4 v174, s[64:65]
	s_addc_u32 s15, s65, 0
	s_add_i32 m0, s9, 0x14000
	v_and_b32_e32 v17, 64, v4
	global_load_lds_dwordx4 v0, s[14:15]
	s_add_i32 m0, s9, 0x16000
	v_and_b32_e32 v18, 60, v3
	global_load_lds_dwordx4 v174, s[14:15]
	v_readlane_b32 s14, v254, 14
	v_bfe_u32 v19, v4, 4, 2
	v_readlane_b32 s15, v254, 15
	s_add_u32 s62, s4, s14
	v_or3_b32 v3, v17, v18, v19
	s_addc_u32 s63, s5, s15
	s_add_i32 s18, s9, 0x2000
	v_lshl_add_u32 v178, v3, 12, v2
	s_mov_b32 m0, s9
	s_add_u32 s14, s62, 0x80000
	global_load_lds_dwordx4 v178, s[62:63]
	s_mov_b32 m0, s18
	s_addc_u32 s15, s63, 0
	s_add_i32 s28, s9, 0x4000
	global_load_lds_dwordx4 v176, s[62:63]
	s_mov_b32 m0, s28
	s_add_i32 s29, s9, 0x6000
	global_load_lds_dwordx4 v178, s[14:15]
	s_mov_b32 m0, s29
	v_mov_b32_e32 v175, v1
	global_load_lds_dwordx4 v176, s[14:15]
	v_mov_b32_e32 v179, v1
	v_mov_b32_e32 v177, v1
	s_cmp_eq_u32 s30, 1
	v_lshl_add_u64 v[8:9], s[64:65], 0, v[0:1]
	v_lshl_add_u64 v[6:7], s[64:65], 0, v[174:175]
	v_lshl_add_u64 v[2:3], s[62:63], 0, v[178:179]
	s_cselect_b64 s[14:15], -1, 0
	s_cmp_lg_u32 s30, 1
	v_lshl_add_u64 v[4:5], s[62:63], 0, v[176:177]
	s_cbranch_scc1 .LBB0_758
	s_barrier

.LBB0_763:
	s_ashr_i32 s51, s50, 31
	s_lshl_b64 s[30:31], s[50:51], 20
	s_add_u32 s52, s4, s30
	s_addc_u32 s53, s5, s31
	s_and_b64 s[30:31], s[38:39], exec
	s_cselect_b32 s51, s53, s63
	s_cselect_b32 s77, s52, s62
	s_ashr_i32 s49, s48, 31
	s_lshl_b64 s[30:31], s[48:49], 20
	s_add_u32 s60, s6, s30
	s_addc_u32 s61, s7, s31
	s_and_b64 s[30:31], s[38:39], exec
	s_cselect_b32 s49, s61, s65
	s_cselect_b32 s78, s60, s64
	s_add_u32 s79, s64, 0x100
	s_addc_u32 s80, s65, 0
	s_mov_b32 s81, -2
	s_waitcnt vmcnt(0)
	s_add_u32 s64, s62, 0x100
	s_addc_u32 s65, s63, 0
	s_add_i32 s30, 0, 0x10000
	s_cmp_eq_u32 s81, 28
	s_cselect_b32 s75, s51, s65
	s_cselect_b32 s74, s77, s64
	s_cselect_b32 s73, s49, s80
	s_cselect_b32 s72, s78, s79
	s_add_i32 s82, 0, 0x14000
	v_add_u32_e32 v142, s30, v220
	v_add_u32_e32 v158, s82, v220
	ds_read_b128 v[130:133], v142
	ds_read_b128 v[134:137], v142 offset:1024
	ds_read_b128 v[138:141], v142 offset:2048
	ds_read_b128 v[142:145], v142 offset:3072
	ds_read_b128 v[146:149], v158
	ds_read_b128 v[150:153], v158 offset:1024
	ds_read_b128 v[154:157], v158 offset:2048
	ds_read_b128 v[158:161], v158 offset:3072
	s_add_i32 m0, s9, 0xc000
	ds_read_b128 v[162:165], v222
	ds_read_b128 v[170:173], v222 offset:1024
	ds_read_b128 v[184:187], v222 offset:2048
	ds_read_b128 v[188:191], v222 offset:3072
	ds_read_b128 v[192:195], v222 offset:4096
	ds_read_b128 v[196:199], v222 offset:5120
	ds_read_b128 v[200:203], v222 offset:6144
	ds_read_b128 v[204:207], v222 offset:7168
	global_load_lds_dwordx4 v182, s[62:63]
	s_add_i32 m0, s9, 0xe000
	s_nop 0
	global_load_lds_dwordx4 v180, s[62:63]
	s_cmp_eq_u32 s98, 16
	s_cbranch_scc1 .Lp8pk_w1_16
	s_waitcnt vmcnt(8)
	s_branch .Lp8pk_w1_done

.Lp8pk_w1_done:
	s_waitcnt lgkmcnt(0)
	s_barrier
	s_setprio 1
	s_waitcnt lgkmcnt(0)
	v_mfma_f32_16x16x32_bf16 v[94:97], v[130:133], v[162:165], 0
	v_mfma_f32_16x16x32_bf16 v[126:129], v[138:141], v[162:165], 0
	v_mfma_f32_16x16x32_bf16 v[90:93], v[130:133], v[184:187], 0
	v_mfma_f32_16x16x32_bf16 v[122:125], v[138:141], v[184:187], 0
	v_mfma_f32_16x16x32_bf16 v[86:89], v[130:133], v[192:195], 0
	v_mfma_f32_16x16x32_bf16 v[118:121], v[138:141], v[192:195], 0
	v_mfma_f32_16x16x32_bf16 v[82:85], v[130:133], v[200:203], 0
	v_mfma_f32_16x16x32_bf16 v[114:117], v[138:141], v[200:203], 0
	v_mfma_f32_16x16x32_bf16 v[94:97], v[134:137], v[170:173], v[94:97]
	v_mfma_f32_16x16x32_bf16 v[126:129], v[142:145], v[170:173], v[126:129]
	v_mfma_f32_16x16x32_bf16 v[90:93], v[134:137], v[188:191], v[90:93]
	v_mfma_f32_16x16x32_bf16 v[122:125], v[142:145], v[188:191], v[122:125]
	v_mfma_f32_16x16x32_bf16 v[86:89], v[134:137], v[196:199], v[86:89]
	v_mfma_f32_16x16x32_bf16 v[118:121], v[142:145], v[196:199], v[118:121]
	v_mfma_f32_16x16x32_bf16 v[82:85], v[134:137], v[204:207], v[82:85]
	v_mfma_f32_16x16x32_bf16 v[114:117], v[142:145], v[204:207], v[114:117]
	s_setprio 0
	s_setprio 1
	v_mfma_f32_16x16x32_bf16 v[78:81], v[146:149], v[162:165], 0
	v_mfma_f32_16x16x32_bf16 v[110:113], v[154:157], v[162:165], 0
	v_mfma_f32_16x16x32_bf16 v[74:77], v[146:149], v[184:187], 0
	v_mfma_f32_16x16x32_bf16 v[106:109], v[154:157], v[184:187], 0
	v_mfma_f32_16x16x32_bf16 v[70:73], v[146:149], v[192:195], 0
	v_mfma_f32_16x16x32_bf16 v[102:105], v[154:157], v[192:195], 0
	v_mfma_f32_16x16x32_bf16 v[66:69], v[146:149], v[200:203], 0
	v_mfma_f32_16x16x32_bf16 v[98:101], v[154:157], v[200:203], 0
	v_mfma_f32_16x16x32_bf16 v[78:81], v[150:153], v[170:173], v[78:81]
	v_mfma_f32_16x16x32_bf16 v[110:113], v[158:161], v[170:173], v[110:113]
	v_mfma_f32_16x16x32_bf16 v[74:77], v[150:153], v[188:191], v[74:77]
	v_mfma_f32_16x16x32_bf16 v[106:109], v[158:161], v[188:191], v[106:109]
	v_mfma_f32_16x16x32_bf16 v[70:73], v[150:153], v[196:199], v[70:73]
	v_mfma_f32_16x16x32_bf16 v[102:105], v[158:161], v[196:199], v[102:105]
	v_mfma_f32_16x16x32_bf16 v[66:69], v[150:153], v[204:207], v[66:69]
	v_mfma_f32_16x16x32_bf16 v[98:101], v[158:161], v[204:207], v[98:101]
	s_setprio 0
	s_barrier
	s_add_i32 s30, s30, s8
	s_mov_b32 m0, s30
	ds_read_b128 v[162:165], v222 offset:16384
	ds_read_b128 v[170:173], v222 offset:17408
	ds_read_b128 v[184:187], v222 offset:18432
	ds_read_b128 v[188:191], v222 offset:19456
	ds_read_b128 v[192:195], v222 offset:20480
	ds_read_b128 v[196:199], v222 offset:21504
	ds_read_b128 v[200:203], v222 offset:22528
	ds_read_b128 v[204:207], v222 offset:23552
	global_load_lds_dwordx4 v0, s[72:73]
	s_add_i32 m0, s30, 0x2000
	s_add_u32 s30, s72, 0x80000
	s_addc_u32 s31, s73, 0
	s_add_i32 s62, s82, s8
	global_load_lds_dwordx4 v174, s[72:73]
	s_mov_b32 m0, s62
	s_nop 0
	global_load_lds_dwordx4 v0, s[30:31]
	s_add_i32 m0, s62, 0x2000
	s_nop 0
	global_load_lds_dwordx4 v174, s[30:31]
	s_mov_b32 m0, s9
	s_nop 0
	global_load_lds_dwordx4 v178, s[74:75]
	s_mov_b32 m0, s18
	s_nop 0
	global_load_lds_dwordx4 v176, s[74:75]
	s_cmp_eq_u32 s98, 16
	s_cbranch_scc1 .Lp8pk_w2_16
	s_waitcnt vmcnt(8)
	s_branch .Lp8pk_w2_done

.Lp8pk_w2_done:
	s_waitcnt lgkmcnt(0)
	s_barrier
	s_setprio 1
	s_waitcnt lgkmcnt(0)
	v_mfma_f32_16x16x32_bf16 v[10:13], v[130:133], v[162:165], 0
	v_mfma_f32_16x16x32_bf16 v[42:45], v[138:141], v[162:165], 0
	v_mfma_f32_16x16x32_bf16 v[18:21], v[130:133], v[184:187], 0
	v_mfma_f32_16x16x32_bf16 v[50:53], v[138:141], v[184:187], 0
	v_mfma_f32_16x16x32_bf16 v[26:29], v[130:133], v[192:195], 0
	v_mfma_f32_16x16x32_bf16 v[58:61], v[138:141], v[192:195], 0
	v_mfma_f32_16x16x32_bf16 v[30:33], v[130:133], v[200:203], 0
	v_mfma_f32_16x16x32_bf16 v[62:65], v[138:141], v[200:203], 0
	v_mfma_f32_16x16x32_bf16 v[10:13], v[134:137], v[170:173], v[10:13]
	v_mfma_f32_16x16x32_bf16 v[42:45], v[142:145], v[170:173], v[42:45]
	v_mfma_f32_16x16x32_bf16 v[18:21], v[134:137], v[188:191], v[18:21]
	v_mfma_f32_16x16x32_bf16 v[50:53], v[142:145], v[188:191], v[50:53]
	v_mfma_f32_16x16x32_bf16 v[26:29], v[134:137], v[196:199], v[26:29]
	v_mfma_f32_16x16x32_bf16 v[58:61], v[142:145], v[196:199], v[58:61]
	v_mfma_f32_16x16x32_bf16 v[30:33], v[134:137], v[204:207], v[30:33]
	v_mfma_f32_16x16x32_bf16 v[62:65], v[142:145], v[204:207], v[62:65]
	s_setprio 0
	s_setprio 1
	v_mfma_f32_16x16x32_bf16 v[2:5], v[146:149], v[162:165], 0
	v_mfma_f32_16x16x32_bf16 v[34:37], v[154:157], v[162:165], 0
	v_mfma_f32_16x16x32_bf16 v[6:9], v[146:149], v[184:187], 0
	v_mfma_f32_16x16x32_bf16 v[38:41], v[154:157], v[184:187], 0
	v_mfma_f32_16x16x32_bf16 v[14:17], v[146:149], v[192:195], 0
	v_mfma_f32_16x16x32_bf16 v[46:49], v[154:157], v[192:195], 0
	v_mfma_f32_16x16x32_bf16 v[22:25], v[146:149], v[200:203], 0
	v_mfma_f32_16x16x32_bf16 v[54:57], v[154:157], v[200:203], 0
	v_mfma_f32_16x16x32_bf16 v[2:5], v[150:153], v[170:173], v[2:5]
	v_mfma_f32_16x16x32_bf16 v[34:37], v[158:161], v[170:173], v[34:37]
	v_mfma_f32_16x16x32_bf16 v[6:9], v[150:153], v[188:191], v[6:9]
	v_mfma_f32_16x16x32_bf16 v[38:41], v[158:161], v[188:191], v[38:41]
	v_mfma_f32_16x16x32_bf16 v[14:17], v[150:153], v[196:199], v[14:17]
	v_mfma_f32_16x16x32_bf16 v[46:49], v[158:161], v[196:199], v[46:49]
	v_mfma_f32_16x16x32_bf16 v[22:25], v[150:153], v[204:207], v[22:25]
	v_mfma_f32_16x16x32_bf16 v[54:57], v[158:161], v[204:207], v[54:57]
	s_setprio 0
	s_barrier
	s_add_i32 s62, 0, 0x18000
	s_add_i32 s63, 0, 0x1c000
	v_add_u32_e32 v142, s62, v220
	v_add_u32_e32 v158, s63, v220
	ds_read_b128 v[130:133], v142
	ds_read_b128 v[134:137], v142 offset:1024
	ds_read_b128 v[138:141], v142 offset:2048
	ds_read_b128 v[142:145], v142 offset:3072
	ds_read_b128 v[146:149], v158
	ds_read_b128 v[150:153], v158 offset:1024
	ds_read_b128 v[154:157], v158 offset:2048
	ds_read_b128 v[158:161], v158 offset:3072
	s_add_u32 s30, s74, 0x80000
	s_addc_u32 s31, s75, 0
	s_mov_b32 m0, s28
	ds_read_b128 v[162:165], v222 offset:32768
	ds_read_b128 v[170:173], v222 offset:33792
	ds_read_b128 v[184:187], v222 offset:34816
	ds_read_b128 v[188:191], v222 offset:35840
	ds_read_b128 v[192:195], v222 offset:36864
	ds_read_b128 v[196:199], v222 offset:37888
	ds_read_b128 v[200:203], v222 offset:38912
	ds_read_b128 v[204:207], v222 offset:39936
	global_load_lds_dwordx4 v178, s[30:31]
	s_mov_b32 m0, s29
	s_nop 0
	global_load_lds_dwordx4 v176, s[30:31]
	s_waitcnt vmcnt(8)
	s_waitcnt lgkmcnt(0)
	s_barrier
	s_setprio 1
	s_waitcnt lgkmcnt(0)
	v_mfma_f32_16x16x32_bf16 v[94:97], v[130:133], v[162:165], v[94:97]
	v_mfma_f32_16x16x32_bf16 v[126:129], v[138:141], v[162:165], v[126:129]
	v_mfma_f32_16x16x32_bf16 v[90:93], v[130:133], v[184:187], v[90:93]
	v_mfma_f32_16x16x32_bf16 v[122:125], v[138:141], v[184:187], v[122:125]
	v_mfma_f32_16x16x32_bf16 v[86:89], v[130:133], v[192:195], v[86:89]
	v_mfma_f32_16x16x32_bf16 v[118:121], v[138:141], v[192:195], v[118:121]
	v_mfma_f32_16x16x32_bf16 v[82:85], v[130:133], v[200:203], v[82:85]
	v_mfma_f32_16x16x32_bf16 v[114:117], v[138:141], v[200:203], v[114:117]
	v_mfma_f32_16x16x32_bf16 v[94:97], v[134:137], v[170:173], v[94:97]
	v_mfma_f32_16x16x32_bf16 v[126:129], v[142:145], v[170:173], v[126:129]
	v_mfma_f32_16x16x32_bf16 v[90:93], v[134:137], v[188:191], v[90:93]
	v_mfma_f32_16x16x32_bf16 v[122:125], v[142:145], v[188:191], v[122:125]
	v_mfma_f32_16x16x32_bf16 v[86:89], v[134:137], v[196:199], v[86:89]
	v_mfma_f32_16x16x32_bf16 v[118:121], v[142:145], v[196:199], v[118:121]
	v_mfma_f32_16x16x32_bf16 v[82:85], v[134:137], v[204:207], v[82:85]
	v_mfma_f32_16x16x32_bf16 v[114:117], v[142:145], v[204:207], v[114:117]
	s_setprio 0
	s_setprio 1
	v_mfma_f32_16x16x32_bf16 v[78:81], v[146:149], v[162:165], v[78:81]
	v_mfma_f32_16x16x32_bf16 v[110:113], v[154:157], v[162:165], v[110:113]
	v_mfma_f32_16x16x32_bf16 v[74:77], v[146:149], v[184:187], v[74:77]
	v_mfma_f32_16x16x32_bf16 v[106:109], v[154:157], v[184:187], v[106:109]
	v_mfma_f32_16x16x32_bf16 v[70:73], v[146:149], v[192:195], v[70:73]
	v_mfma_f32_16x16x32_bf16 v[102:105], v[154:157], v[192:195], v[102:105]
	v_mfma_f32_16x16x32_bf16 v[66:69], v[146:149], v[200:203], v[66:69]
	v_mfma_f32_16x16x32_bf16 v[98:101], v[154:157], v[200:203], v[98:101]
	v_mfma_f32_16x16x32_bf16 v[78:81], v[150:153], v[170:173], v[78:81]
	v_mfma_f32_16x16x32_bf16 v[110:113], v[158:161], v[170:173], v[110:113]
	v_mfma_f32_16x16x32_bf16 v[74:77], v[150:153], v[188:191], v[74:77]
	v_mfma_f32_16x16x32_bf16 v[106:109], v[158:161], v[188:191], v[106:109]
	v_mfma_f32_16x16x32_bf16 v[70:73], v[150:153], v[196:199], v[70:73]
	v_mfma_f32_16x16x32_bf16 v[102:105], v[158:161], v[196:199], v[102:105]
	v_mfma_f32_16x16x32_bf16 v[66:69], v[150:153], v[204:207], v[66:69]
	v_mfma_f32_16x16x32_bf16 v[98:101], v[158:161], v[204:207], v[98:101]
	s_setprio 0
	s_barrier
	s_add_i32 s30, s62, s8
	s_add_i32 m0, s30, 0xffffff80
	ds_read_b128 v[162:165], v222 offset:49152
	ds_read_b128 v[170:173], v222 offset:50176
	ds_read_b128 v[184:187], v222 offset:51200
	ds_read_b128 v[188:191], v222 offset:52224
	ds_read_b128 v[192:195], v222 offset:53248
	ds_read_b128 v[196:199], v222 offset:54272
	ds_read_b128 v[200:203], v222 offset:55296
	ds_read_b128 v[204:207], v222 offset:56320
	global_load_lds_dwordx4 v0, s[72:73] offset:128
	s_add_i32 m0, s30, 0x1f80
	s_add_u32 s30, s72, 0x80080
	s_addc_u32 s31, s73, 0
	s_add_i32 s62, s63, s8
	global_load_lds_dwordx4 v174, s[72:73] offset:128
	s_mov_b32 m0, s62
	s_nop 0
	global_load_lds_dwordx4 v0, s[30:31]
	s_add_i32 m0, s62, 0x2000
	s_nop 0
	global_load_lds_dwordx4 v174, s[30:31]
	s_add_i32 m0, s54, 0xffffff80
	s_nop 0
	global_load_lds_dwordx4 v178, s[74:75] offset:128
	s_add_i32 m0, s55, 0xffffff80
	s_nop 0
	global_load_lds_dwordx4 v176, s[74:75] offset:128
	s_waitcnt vmcnt(8)
	s_waitcnt lgkmcnt(0)
	s_barrier
	s_setprio 1
	s_waitcnt lgkmcnt(0)
	v_mfma_f32_16x16x32_bf16 v[10:13], v[130:133], v[162:165], v[10:13]
	v_mfma_f32_16x16x32_bf16 v[42:45], v[138:141], v[162:165], v[42:45]
	v_mfma_f32_16x16x32_bf16 v[18:21], v[130:133], v[184:187], v[18:21]
	v_mfma_f32_16x16x32_bf16 v[50:53], v[138:141], v[184:187], v[50:53]
	v_mfma_f32_16x16x32_bf16 v[26:29], v[130:133], v[192:195], v[26:29]
	v_mfma_f32_16x16x32_bf16 v[58:61], v[138:141], v[192:195], v[58:61]
	v_mfma_f32_16x16x32_bf16 v[30:33], v[130:133], v[200:203], v[30:33]
	v_mfma_f32_16x16x32_bf16 v[62:65], v[138:141], v[200:203], v[62:65]
	v_mfma_f32_16x16x32_bf16 v[10:13], v[134:137], v[170:173], v[10:13]
	v_mfma_f32_16x16x32_bf16 v[42:45], v[142:145], v[170:173], v[42:45]
	v_mfma_f32_16x16x32_bf16 v[18:21], v[134:137], v[188:191], v[18:21]
	v_mfma_f32_16x16x32_bf16 v[50:53], v[142:145], v[188:191], v[50:53]
	v_mfma_f32_16x16x32_bf16 v[26:29], v[134:137], v[196:199], v[26:29]
	v_mfma_f32_16x16x32_bf16 v[58:61], v[142:145], v[196:199], v[58:61]
	v_mfma_f32_16x16x32_bf16 v[30:33], v[134:137], v[204:207], v[30:33]
	v_mfma_f32_16x16x32_bf16 v[62:65], v[142:145], v[204:207], v[62:65]
	s_setprio 0
	s_setprio 1
	v_mfma_f32_16x16x32_bf16 v[2:5], v[146:149], v[162:165], v[2:5]
	v_mfma_f32_16x16x32_bf16 v[34:37], v[154:157], v[162:165], v[34:37]
	v_mfma_f32_16x16x32_bf16 v[6:9], v[146:149], v[184:187], v[6:9]
	v_mfma_f32_16x16x32_bf16 v[38:41], v[154:157], v[184:187], v[38:41]
	v_mfma_f32_16x16x32_bf16 v[14:17], v[146:149], v[192:195], v[14:17]
	v_mfma_f32_16x16x32_bf16 v[46:49], v[154:157], v[192:195], v[46:49]
	v_mfma_f32_16x16x32_bf16 v[22:25], v[146:149], v[200:203], v[22:25]
	v_mfma_f32_16x16x32_bf16 v[54:57], v[154:157], v[200:203], v[54:57]
	v_mfma_f32_16x16x32_bf16 v[2:5], v[150:153], v[170:173], v[2:5]
	v_mfma_f32_16x16x32_bf16 v[34:37], v[158:161], v[170:173], v[34:37]
	v_mfma_f32_16x16x32_bf16 v[6:9], v[150:153], v[188:191], v[6:9]
	v_mfma_f32_16x16x32_bf16 v[38:41], v[158:161], v[188:191], v[38:41]
	v_mfma_f32_16x16x32_bf16 v[14:17], v[150:153], v[196:199], v[14:17]
	v_mfma_f32_16x16x32_bf16 v[46:49], v[158:161], v[196:199], v[46:49]
	v_mfma_f32_16x16x32_bf16 v[22:25], v[150:153], v[204:207], v[22:25]
	v_mfma_f32_16x16x32_bf16 v[54:57], v[158:161], v[204:207], v[54:57]
	s_setprio 0
	s_barrier
	s_add_i32 s81, s81, 2
	s_add_u32 s79, s79, 0x100
	s_addc_u32 s80, s80, 0
	s_cmp_gt_u32 s81, 29
	s_mov_b64 s[62:63], s[64:65]

.LBB0_767:
	s_mov_b32 s98, 16
	v_lshl_add_u32 v188, s76, 7, v221
	v_ashrrev_i32_e32 v189, 31, v188
	v_lshlrev_b64 v[130:131], 2, v[188:189]
	v_lshl_add_u64 v[132:133], s[20:21], 0, v[130:131]
	v_lshl_add_u64 v[134:135], s[44:45], 0, v[130:131]
	v_lshl_add_u64 v[136:137], s[46:47], 0, v[130:131]
	v_lshl_add_u64 v[130:131], s[22:23], 0, v[130:131]
	global_load_dwordx4 v[158:161], v[132:133], off offset:16
	global_load_dwordx4 v[142:145], v[132:133], off
	global_load_dwordx4 v[154:157], v[134:135], off offset:16
	global_load_dwordx4 v[138:141], v[134:135], off
	global_load_dwordx4 v[150:153], v[136:137], off offset:16
	s_nop 0
	global_load_dwordx4 v[134:137], v[136:137], off
	s_nop 0
	global_load_dwordx4 v[146:149], v[130:131], off offset:16
	s_nop 0
	global_load_dwordx4 v[130:133], v[130:131], off
	v_mov_b32_e32 v190, v1
	v_mov_b32_e32 v194, v1
	v_mov_b32_e32 v191, v1
	v_mov_b32_e32 v195, v1
	v_mov_b32_e32 v192, v1
	v_mov_b32_e32 v196, v1
	v_mov_b32_e32 v193, v1
	v_mov_b32_e32 v197, v1
	v_mov_b32_dpp v190, v82 row_shr:1 row_mask:0xf bank_mask:0xf
	v_mov_b32_dpp v194, v86 row_shr:1 row_mask:0xf bank_mask:0xf
	v_mov_b32_dpp v191, v83 row_shr:1 row_mask:0xf bank_mask:0xf
	v_mov_b32_dpp v195, v87 row_shr:1 row_mask:0xf bank_mask:0xf
	v_mov_b32_dpp v192, v84 row_shr:1 row_mask:0xf bank_mask:0xf
	v_mov_b32_dpp v196, v88 row_shr:1 row_mask:0xf bank_mask:0xf
	v_mov_b32_dpp v193, v85 row_shr:1 row_mask:0xf bank_mask:0xf
	v_mov_b32_dpp v197, v89 row_shr:1 row_mask:0xf bank_mask:0xf
	v_cmp_lt_i32_e32 vcc, 14, v218
	s_mov_b64 s[62:63], 0
	s_and_saveexec_b64 s[30:31], vcc
	s_xor_b64 s[64:65], exec, s[30:31]
	s_mov_b64 s[62:63], exec
	v_cvt_pk_bf16_f32 v162, v86, v87
	v_cvt_pk_bf16_f32 v163, v88, v89
	v_cvt_pk_bf16_f32 v164, v82, v83
	v_cvt_pk_bf16_f32 v165, v84, v85
	s_or_saveexec_b64 s[64:65], s[64:65]
	s_lshl_b32 s49, s69, 8
	s_add_i32 s49, s49, s35
	v_ashrrev_i32_e32 v184, 2, v188
	s_ashr_i32 s30, s49, 6
	v_ashrrev_i32_e32 v185, 31, v184
	v_mad_i64_i32 v[166:167], s[72:73], s30, v235, v[184:185]
	v_lshlrev_b64 v[186:187], 4, v[166:167]
	v_mov_b64_e32 v[198:199], 0x72c00000
	s_xor_b64 exec, exec, s[64:65]
	s_cbranch_execz .LBB0_773
	v_cmp_eq_u32_e32 vcc, 0, v218
	s_mov_b64 s[74:75], s[62:63]
	s_and_saveexec_b64 s[72:73], vcc
	s_cbranch_execz .LBB0_772
	v_cvt_pk_bf16_f32 v170, v94, v95
	v_cvt_pk_bf16_f32 v171, v96, v97
	v_cvt_pk_bf16_f32 v172, v90, v91
	v_cvt_pk_bf16_f32 v173, v92, v93
	v_cvt_pk_bf16_f32 v162, v78, v79
	v_cvt_pk_bf16_f32 v163, v80, v81
	v_cvt_pk_bf16_f32 v164, v74, v75
	v_cvt_pk_bf16_f32 v165, v76, v77
	v_lshl_add_u64 v[166:167], s[40:41], 0, v[186:187]
	s_or_b64 s[74:75], s[62:63], exec
	global_store_dwordx4 v[166:167], v[170:173], off
